# rstd-table fill of P1/P3/P8 moved after the first eight prologue LDS-DMA loads so its global-load latency overlaps the first tile fetch
# speedup vs baseline: 1.0069x; 1.0069x over previous
; #define LAS __attribute__((address_space(3)))
; __device__ __forceinline__ float row_rstd(const float* ss, int row) {
;     const f32x4* p = (const f32x4*)(ss + (size_t)row * 16);
;     const f32x4 a = p[0], b = p[1], c = p[2], d = p[3];
;     const float s = (((a[0] + a[1]) + (a[2] + a[3])) + ((b[0] + b[1]) + (b[2] + b[3]))) + (((c[0] + c[1]) + (c[2] + c[3])) + ((d[0] + d[1]) + (d[2] + d[3])));
;     return 1.0f / sqrtf(s * (1.0f / 1024.0f) + 1e-6f);
; }
; __device__ __forceinline__ int fill_rtab(const pg8::StaticOrder& so, const float* ss, LAS float* rtab) {
;     pg8::Unit u0; int pm0 = -1;
;     if (so.next(0, u0)) { pm0 = u0.pm; if (threadIdx.x < 256) rtab[threadIdx.x] = pg8::row_rstd(ss, pm0 * 256 + (int)threadIdx.x); }
;     __syncthreads();
;     return pm0;
; }
.LBB0_122:
	s_mov_b32 s2, s3

; #define PG8_STAGE(bufoff, gbase, voff) do { _Pragma("unroll") for (int _i = 0; _i < 2; ++_i) \
;         __builtin_amdgcn_global_load_lds((const unsigned*)((const char*)(gbase) + (voff)[_i]), (PG8_LAS unsigned*)(lds + (bufoff) + ldsw + _i * 8192), 16, 0, 0); } while (0)
; __device__ __forceinline__ float row_rstd(const float* ss, int row) {
;     const f32x4* p = (const f32x4*)(ss + (size_t)row * 16);
;     const f32x4 a = p[0], b = p[1], c = p[2], d = p[3];
;     const float s = (((a[0] + a[1]) + (a[2] + a[3])) + ((b[0] + b[1]) + (b[2] + b[3]))) + (((c[0] + c[1]) + (c[2] + c[3])) + ((d[0] + d[1]) + (d[2] + d[3])));
;     return 1.0f / sqrtf(s * (1.0f / 1024.0f) + 1e-6f);
; }
; template <class Epi, class Sched, bool ALIGN_EPI = false, bool SP2 = false>
; __device__ __forceinline__ void gemm_phase(PG8_LAS unsigned char* lds, const Gemm g, const Sched& S, const Epi& E) {
;     ...
;     for (int i = 0; i < 2; ++i) { int R, C; stage_rc(tid * 16 + i * 8192, R, C); const int Rb = Epi::PERM ? ((R & ~31) + perm32(R & 31)) : R;
;         voffA[i] = (unsigned)(R * K + C) * 2u; voffB[i] = (unsigned)(Rb * K + C) * 2u; }
;     const size_t kstep = (size_t)(BK * 2);
;     const size_t hstep = (size_t)HALF * K * 2;
;     const size_t tstep = 2 * hstep;
;     const unsigned ldsw = (unsigned)wid * 1024u;
;     const int aoff = lds_byte(wr * 64 + fr, fq * 8), boff = lds_byte(wc * 32 + fr, fq * 8);
;     ...
;     Unit cur, nxt; int ui = 0;
;     if (!S.next(0, cur)) return;
;     f32x4 acc[2][2][4][2];
; #pragma unroll
;     for (int a = 0; a < 2; ++a)
; #pragma unroll
;         for (int b = 0; b < 2; ++b)
; #pragma unroll
;             for (int m = 0; m < 4; ++m)
; #pragma unroll
;                 for (int n = 0; n < 2; ++n) acc[a][b][m][n] = (f32x4){0.f, 0.f, 0.f, 0.f};
;     bf16x8 At[4][2], B0[2][2], B1[2][2];
;     const char* cA = (const char*)g.A + (size_t)cur.pm * tstep; const char* cB = (const char*)g.Bt + (size_t)cur.pn * tstep;
;     S.a_ready(cur);
;     if constexpr (SP2) {
;         PG8_STAGE(PG8_SB(0, 0), cB, voffB); PG8_STAGE(PG8_SB(0, 1), cB + hstep, voffB); PG8_STAGE(PG8_SA(0, 0), cA, voffA); PG8_STAGE(PG8_SA(0, 1), cA + hstep, voffA);
.LBB0_125:
	v_lshlrev_b32_e32 v247, 4, v152
	v_and_b32_e32 v0, 32, v152
	v_bitop3_b32 v232, v247, v0, 48 bitop3:0x6c
	v_lshrrev_b32_e32 v0, 5, v152
	v_lshrrev_b32_e32 v2, 1, v152
	v_bfe_u32 v235, v152, 2, 4
	v_and_b32_e32 v0, 4, v0
	v_bfe_u32 v1, v152, 2, 2
	v_and_b32_e32 v236, 24, v2
	v_lshrrev_b32_e32 v246, 3, v152
	s_movk_i32 s1, 0x70
	v_or3_b32 v0, v0, v1, v236
	v_and_or_b32 v144, v246, s1, v235
	s_movk_i32 s1, 0x60
	v_add_u32_e32 v237, 0x2000, v247
	v_and_or_b32 v143, v246, s1, v0
	v_lshrrev_b32_e32 v1, 7, v237
	s_movk_i32 s1, 0xf0
	v_and_or_b32 v146, v1, s1, v235
	s_movk_i32 s1, 0xe0
	v_and_or_b32 v145, v1, s1, v0
	v_lshlrev_b32_e32 v0, 6, v152
	s_add_u32 s76, s72, 0xa800000
	v_and_b32_e32 v233, 64, v152
	v_and_b32_e32 v141, 0x3c0, v0
	v_lshlrev_b32_e32 v0, 2, v152
	s_addc_u32 s77, s73, 0
	v_readlane_b32 s8, v255, 5
	v_or_b32_e32 v140, v232, v233
	v_lshlrev_b32_e32 v254, 1, v236
	v_and_b32_e32 v142, 32, v0
	s_add_u32 s78, s72, 0x3000000
	v_readlane_b32 s9, v255, 6
	v_lshl_or_b32 v156, v144, 11, v140
	v_lshl_or_b32 v158, v143, 11, v140
	v_lshl_or_b32 v160, v146, 11, v140
	v_lshl_or_b32 v162, v145, 11, v140
	v_and_b32_e32 v234, 15, v152
	s_addc_u32 s79, s73, 0
	s_and_b64 vcc, exec, s[8:9]
	v_bitop3_b32 v231, v254, v142, v141 bitop3:0x36
	s_cbranch_vccnz .LBB0_173
	s_lshr_b32 s10, s4, 6
	s_ashr_i32 s1, s0, 31
	s_ashr_i32 s7, s6, 31
	s_lshr_b32 s5, s4, 8
	s_lshl_b32 s3, s10, 10
	s_lshl_b64 s[8:9], s[0:1], 19
	s_lshl_b64 s[12:13], s[6:7], 19
	s_add_u32 s36, s24, s12
	s_addc_u32 s37, s25, s13
	s_add_i32 s33, s3, 0
	s_add_i32 m0, s33, 0x10000
	v_mov_b32_e32 v159, 0
	global_load_lds_dwordx4 v158, s[36:37]
	s_add_i32 m0, s33, 0x12000
	s_add_u32 s12, s36, 0x40000
	global_load_lds_dwordx4 v162, s[36:37]
	s_addc_u32 s13, s37, 0
	s_add_i32 m0, s33, 0x14000
	v_mov_b32_e32 v163, v159
	global_load_lds_dwordx4 v158, s[12:13]
	s_add_i32 m0, s33, 0x16000
	s_add_u32 s34, s76, s8
	s_addc_u32 s35, s77, s9
	s_add_i32 s40, s33, 0x2000
	global_load_lds_dwordx4 v162, s[12:13]
	s_mov_b32 m0, s33
	s_add_u32 s8, s34, 0x40000
	global_load_lds_dwordx4 v156, s[34:35]
	s_mov_b32 m0, s40
	s_addc_u32 s9, s35, 0
	s_add_i32 s41, s33, 0x4000
	global_load_lds_dwordx4 v160, s[34:35]
	s_mov_b32 m0, s41
	s_add_i32 s42, s33, 0x6000
	global_load_lds_dwordx4 v156, s[8:9]
	s_mov_b32 m0, s42
	v_mov_b32_e32 v157, v159
	global_load_lds_dwordx4 v160, s[8:9]
	s_movk_i32 s98, 0x100
	v_cmp_gt_u32_e32 vcc, s98, v152
	s_and_saveexec_b64 s[100:101], vcc
	s_cbranch_execz .Lrtab_p1
	v_lshl_or_b32 v188, s0, 8, v152
	v_ashrrev_i32_e32 v189, 31, v188
	v_lshlrev_b64 v[188:189], 6, v[188:189]
	v_lshl_add_u64 v[200:201], s[72:73], 0, v[188:189]
	global_load_dwordx4 v[188:191], v[200:201], off
	global_load_dwordx4 v[192:195], v[200:201], off offset:32
	global_load_dwordx4 v[196:199], v[200:201], off offset:16
	s_nop 0
	global_load_dwordx4 v[200:203], v[200:201], off offset:48
	v_mov_b32_e32 v206, 0x358637bd
	s_mov_b32 s98, 0xf800000
	s_waitcnt vmcnt(3)
	v_mov_b32_e32 v204, v188
	s_waitcnt vmcnt(2)
	v_mov_b32_e32 v205, v192
	v_mov_b32_e32 v192, v189
	v_mov_b32_e32 v188, v190
	v_mov_b32_e32 v189, v194
	v_mov_b32_e32 v194, v191
	s_waitcnt vmcnt(1)
	v_mov_b32_e32 v190, v196
	s_waitcnt vmcnt(0)
	v_mov_b32_e32 v191, v200
	v_mov_b32_e32 v200, v197
	v_mov_b32_e32 v196, v198
	v_mov_b32_e32 v197, v202
	v_mov_b32_e32 v202, v199
	v_pk_add_f32 v[192:193], v[204:205], v[192:193]
	v_pk_add_f32 v[188:189], v[188:189], v[194:195]
	v_pk_add_f32 v[190:191], v[190:191], v[200:201]
	v_pk_add_f32 v[194:195], v[196:197], v[202:203]
	v_pk_add_f32 v[188:189], v[192:193], v[188:189]
	v_pk_add_f32 v[190:191], v[190:191], v[194:195]
	s_nop 0
	v_pk_add_f32 v[188:189], v[188:189], v[190:191]
	v_mov_b32_e32 v190, 0x260
	v_add_f32_e32 v188, v188, v189
	v_fmac_f32_e32 v206, 0x3a800000, v188
	v_mul_f32_e32 v188, 0x4f800000, v206
	v_cmp_gt_f32_e32 vcc, s98, v206
	s_nop 1
	v_cndmask_b32_e32 v188, v206, v188, vcc
	v_sqrt_f32_e32 v189, v188
	s_nop 0
	v_add_u32_e32 v191, -1, v189
	v_add_u32_e32 v192, 1, v189
	v_fma_f32 v193, -v191, v189, v188
	v_fma_f32 v194, -v192, v189, v188
	v_cmp_ge_f32_e64 s[98:99], 0, v193
	s_nop 1
	v_cndmask_b32_e64 v189, v189, v191, s[98:99]
	v_cmp_lt_f32_e64 s[98:99], 0, v194
	s_nop 1
	v_cndmask_b32_e64 v189, v189, v192, s[98:99]
	v_mul_f32_e32 v191, 0x37800000, v189
	v_cndmask_b32_e32 v189, v189, v191, vcc
	v_cmp_class_f32_e32 vcc, v188, v190
	v_lshl_add_u32 v191, v152, 2, 0
	s_nop 0
	v_cndmask_b32_e32 v188, v189, v188, vcc
	v_div_scale_f32 v189, s[98:99], v188, v188, 1.0
	v_rcp_f32_e32 v190, v189
	v_div_scale_f32 v192, vcc, 1.0, v188, 1.0
	v_fma_f32 v193, -v189, v190, 1.0
	v_fmac_f32_e32 v190, v193, v190
	v_mul_f32_e32 v193, v192, v190
	v_fma_f32 v194, -v189, v193, v192
	v_fmac_f32_e32 v193, v194, v190
	v_fma_f32 v189, -v189, v193, v192
	v_div_fmas_f32 v189, v189, v190, v193
	v_div_fixup_f32 v188, v189, v188, 1.0
	v_add_u32_e32 v189, 0x20100, v191
	ds_write_b32 v189, v188
.Lrtab_p1:
	s_or_b64 exec, exec, s[100:101]
	v_mov_b32_e32 v161, v159
	s_cmp_eq_u32 s5, 1
	s_mov_b32 s43, 0
	v_lshl_add_u64 v[6:7], s[36:37], 0, v[158:159]
	v_lshl_add_u64 v[4:5], s[36:37], 0, v[162:163]
	v_lshl_add_u64 v[0:1], s[34:35], 0, v[156:157]
	s_cselect_b64 s[8:9], -1, 0
	s_cmp_lg_u32 s5, 1
	v_lshl_add_u64 v[2:3], s[34:35], 0, v[160:161]
	s_cbranch_scc1 .LBB0_128
	s_barrier

; #define PG8_STAGE(bufoff, gbase, voff) do { _Pragma("unroll") for (int _i = 0; _i < 2; ++_i) \
;         __builtin_amdgcn_global_load_lds((const unsigned*)((const char*)(gbase) + (voff)[_i]), (PG8_LAS unsigned*)(lds + (bufoff) + ldsw + _i * 8192), 16, 0, 0); } while (0)
; #define PG8_WAIT_V(n) asm volatile("s_waitcnt vmcnt(" #n ")" ::: "memory")
; #define PG8_BAR __builtin_amdgcn_s_barrier()
; __device__ __forceinline__ float row_rstd(const float* ss, int row) {
;     const f32x4* p = (const f32x4*)(ss + (size_t)row * 16);
;     const f32x4 a = p[0], b = p[1], c = p[2], d = p[3];
;     const float s = (((a[0] + a[1]) + (a[2] + a[3])) + ((b[0] + b[1]) + (b[2] + b[3]))) + (((c[0] + c[1]) + (c[2] + c[3])) + ((d[0] + d[1]) + (d[2] + d[3])));
;     return 1.0f / sqrtf(s * (1.0f / 1024.0f) + 1e-6f);
; }
; template <class Epi, class Sched, bool ALIGN_EPI = false, bool SP2 = false>
; __device__ __forceinline__ void gemm_phase(PG8_LAS unsigned char* lds, const Gemm g, const Sched& S, const Epi& E) {
;     ...
;     const char* cA = (const char*)g.A + (size_t)cur.pm * tstep; const char* cB = (const char*)g.Bt + (size_t)cur.pn * tstep;
;     S.a_ready(cur);
;     if constexpr (SP2) {
;         PG8_STAGE(PG8_SB(0, 0), cB, voffB); PG8_STAGE(PG8_SB(0, 1), cB + hstep, voffB); PG8_STAGE(PG8_SA(0, 0), cA, voffA); PG8_STAGE(PG8_SA(0, 1), cA + hstep, voffA);
;         if (wr == 1) PG8_BAR;
;         PG8_WAIT_V(2); PG8_BAR;
;         PG8_STAGE(PG8_SB(1, 0), cB + kstep, voffB); PG8_STAGE(PG8_SA(1, 0), cA + kstep, voffA); PG8_STAGE(PG8_SB(1, 1), cB + hstep + kstep, voffB);
.LBB0_455:
	s_add_u32 s54, s72, 0x400000
	s_addc_u32 s55, s73, 0
	s_and_b64 vcc, exec, s[0:1]
	s_cbranch_vccnz .LBB0_541
	s_lshr_b32 s6, s8, 6
	s_lshr_b32 s9, s8, 8
	s_lshl_b32 s3, s6, 10
	s_add_u32 s33, s72, 0x2800000
	s_addc_u32 s36, s73, 0
	s_ashr_i32 s13, s12, 31
	s_ashr_i32 s29, s28, 31
	s_lshl_b64 s[0:1], s[12:13], 19
	s_lshl_b64 s[4:5], s[28:29], 19
	s_add_u32 s30, s33, s4
	s_addc_u32 s31, s36, s5
	s_add_i32 s29, s3, 0
	s_add_i32 m0, s29, 0x10000
	v_mov_b32_e32 v159, 0
	global_load_lds_dwordx4 v158, s[30:31]
	s_add_i32 m0, s29, 0x12000
	s_add_u32 s4, s30, 0x40000
	global_load_lds_dwordx4 v162, s[30:31]
	s_addc_u32 s5, s31, 0
	s_add_i32 m0, s29, 0x14000
	v_mov_b32_e32 v163, v159
	global_load_lds_dwordx4 v158, s[4:5]
	s_add_i32 m0, s29, 0x16000
	s_add_u32 s0, s76, s0
	s_addc_u32 s1, s77, s1
	s_add_i32 s37, s29, 0x2000
	global_load_lds_dwordx4 v162, s[4:5]
	s_mov_b32 m0, s29
	s_add_u32 s4, s0, 0x40000
	global_load_lds_dwordx4 v156, s[0:1]
	s_mov_b32 m0, s37
	s_addc_u32 s5, s1, 0
	s_add_i32 s38, s29, 0x4000
	global_load_lds_dwordx4 v160, s[0:1]
	s_mov_b32 m0, s38
	s_add_i32 s39, s29, 0x6000
	global_load_lds_dwordx4 v156, s[4:5]
	s_mov_b32 m0, s39
	v_mov_b32_e32 v157, v159
	global_load_lds_dwordx4 v160, s[4:5]
	s_movk_i32 s98, 0x100
	v_cmp_gt_u32_e32 vcc, s98, v152
	s_and_saveexec_b64 s[100:101], vcc
	s_cbranch_execz .Lrtab_p3
	v_lshl_or_b32 v188, s12, 8, v152
	v_ashrrev_i32_e32 v189, 31, v188
	v_lshlrev_b64 v[188:189], 6, v[188:189]
	v_lshl_add_u64 v[200:201], s[14:15], 0, v[188:189]
	global_load_dwordx4 v[188:191], v[200:201], off
	global_load_dwordx4 v[192:195], v[200:201], off offset:32
	global_load_dwordx4 v[196:199], v[200:201], off offset:16
	s_nop 0
	global_load_dwordx4 v[200:203], v[200:201], off offset:48
	v_mov_b32_e32 v206, 0x358637bd
	s_mov_b32 s98, 0xf800000
	s_waitcnt vmcnt(3)
	v_mov_b32_e32 v204, v188
	s_waitcnt vmcnt(2)
	v_mov_b32_e32 v205, v192
	v_mov_b32_e32 v192, v189
	v_mov_b32_e32 v188, v190
	v_mov_b32_e32 v189, v194
	v_mov_b32_e32 v194, v191
	s_waitcnt vmcnt(1)
	v_mov_b32_e32 v190, v196
	s_waitcnt vmcnt(0)
	v_mov_b32_e32 v191, v200
	v_mov_b32_e32 v200, v197
	v_mov_b32_e32 v196, v198
	v_mov_b32_e32 v197, v202
	v_mov_b32_e32 v202, v199
	v_pk_add_f32 v[192:193], v[204:205], v[192:193]
	v_pk_add_f32 v[188:189], v[188:189], v[194:195]
	v_pk_add_f32 v[190:191], v[190:191], v[200:201]
	v_pk_add_f32 v[194:195], v[196:197], v[202:203]
	v_pk_add_f32 v[188:189], v[192:193], v[188:189]
	v_pk_add_f32 v[190:191], v[190:191], v[194:195]
	s_nop 0
	v_pk_add_f32 v[188:189], v[188:189], v[190:191]
	v_mov_b32_e32 v190, 0x260
	v_add_f32_e32 v188, v188, v189
	v_fmac_f32_e32 v206, 0x3a800000, v188
	v_mul_f32_e32 v188, 0x4f800000, v206
	v_cmp_gt_f32_e32 vcc, s98, v206
	s_nop 1
	v_cndmask_b32_e32 v188, v206, v188, vcc
	v_sqrt_f32_e32 v189, v188
	s_nop 0
	v_add_u32_e32 v191, -1, v189
	v_add_u32_e32 v192, 1, v189
	v_fma_f32 v193, -v191, v189, v188
	v_fma_f32 v194, -v192, v189, v188
	v_cmp_ge_f32_e64 s[98:99], 0, v193
	s_nop 1
	v_cndmask_b32_e64 v189, v189, v191, s[98:99]
	v_cmp_lt_f32_e64 s[98:99], 0, v194
	s_nop 1
	v_cndmask_b32_e64 v189, v189, v192, s[98:99]
	v_mul_f32_e32 v191, 0x37800000, v189
	v_cndmask_b32_e32 v189, v189, v191, vcc
	v_cmp_class_f32_e32 vcc, v188, v190
	v_lshl_add_u32 v191, v152, 2, 0
	s_nop 0
	v_cndmask_b32_e32 v188, v189, v188, vcc
	v_div_scale_f32 v189, s[98:99], v188, v188, 1.0
	v_rcp_f32_e32 v190, v189
	v_div_scale_f32 v192, vcc, 1.0, v188, 1.0
	v_fma_f32 v193, -v189, v190, 1.0
	v_fmac_f32_e32 v190, v193, v190
	v_mul_f32_e32 v193, v192, v190
	v_fma_f32 v194, -v189, v193, v192
	v_fmac_f32_e32 v193, v194, v190
	v_fma_f32 v189, -v189, v193, v192
	v_div_fmas_f32 v189, v189, v190, v193
	v_div_fixup_f32 v188, v189, v188, 1.0
	v_add_u32_e32 v189, 0x20100, v191
	ds_write_b32 v189, v188
.Lrtab_p3:
	s_or_b64 exec, exec, s[100:101]
	v_mov_b32_e32 v161, v159
	s_cmp_eq_u32 s9, 1
	s_mov_b32 s40, 0
	v_lshl_add_u64 v[6:7], s[30:31], 0, v[158:159]
	v_lshl_add_u64 v[4:5], s[30:31], 0, v[162:163]
	v_lshl_add_u64 v[0:1], s[0:1], 0, v[156:157]
	s_cselect_b64 s[4:5], -1, 0
	s_cmp_lg_u32 s9, 1
	v_lshl_add_u64 v[2:3], s[0:1], 0, v[160:161]
	s_cbranch_scc1 .LBB0_458
	s_barrier

; #define PG8_STAGE(bufoff, gbase, voff) do { _Pragma("unroll") for (int _i = 0; _i < 2; ++_i) \
;         __builtin_amdgcn_global_load_lds((const unsigned*)((const char*)(gbase) + (voff)[_i]), (PG8_LAS unsigned*)(lds + (bufoff) + ldsw + _i * 8192), 16, 0, 0); } while (0)
; #define PG8_WAIT_V(n) asm volatile("s_waitcnt vmcnt(" #n ")" ::: "memory")
; #define PG8_BAR __builtin_amdgcn_s_barrier()
; __device__ __forceinline__ float row_rstd(const float* ss, int row) {
;     const f32x4* p = (const f32x4*)(ss + (size_t)row * 16);
;     const f32x4 a = p[0], b = p[1], c = p[2], d = p[3];
;     const float s = (((a[0] + a[1]) + (a[2] + a[3])) + ((b[0] + b[1]) + (b[2] + b[3]))) + (((c[0] + c[1]) + (c[2] + c[3])) + ((d[0] + d[1]) + (d[2] + d[3])));
;     return 1.0f / sqrtf(s * (1.0f / 1024.0f) + 1e-6f);
; }
; template <class Epi, class Sched, bool ALIGN_EPI = false, bool SP2 = false>
; __device__ __forceinline__ void gemm_phase(PG8_LAS unsigned char* lds, const Gemm g, const Sched& S, const Epi& E) {
;     ...
;     const char* cA = (const char*)g.A + (size_t)cur.pm * tstep; const char* cB = (const char*)g.Bt + (size_t)cur.pn * tstep;
;     S.a_ready(cur);
;     if constexpr (SP2) {
;         PG8_STAGE(PG8_SB(0, 0), cB, voffB); PG8_STAGE(PG8_SB(0, 1), cB + hstep, voffB); PG8_STAGE(PG8_SA(0, 0), cA, voffA); PG8_STAGE(PG8_SA(0, 1), cA + hstep, voffA);
;         if (wr == 1) PG8_BAR;
;         PG8_WAIT_V(2); PG8_BAR;
;         PG8_STAGE(PG8_SB(1, 0), cB + kstep, voffB); PG8_STAGE(PG8_SA(1, 0), cA + kstep, voffA); PG8_STAGE(PG8_SB(1, 1), cB + hstep + kstep, voffB);
.LBB0_1313:
	s_and_b64 vcc, exec, s[48:49]
	s_cbranch_vccnz .LBB0_1361
	s_lshr_b32 s6, s8, 6
	s_lshr_b32 s9, s8, 8
	s_lshl_b32 s3, s6, 10
	s_add_u32 s30, s72, 0x1700000
	s_addc_u32 s31, s73, 0
	s_ashr_i32 s1, s0, 31
	s_ashr_i32 s11, s10, 31
	s_lshl_b64 s[4:5], s[0:1], 19
	s_lshl_b64 s[14:15], s[10:11], 19
	s_add_u32 s26, s30, s14
	s_addc_u32 s27, s31, s15
	s_add_i32 s33, s3, 0
	s_add_i32 m0, s33, 0x10000
	v_mov_b32_e32 v159, 0
	global_load_lds_dwordx4 v158, s[26:27]
	s_add_i32 m0, s33, 0x12000
	s_add_u32 s14, s26, 0x40000
	global_load_lds_dwordx4 v162, s[26:27]
	s_addc_u32 s15, s27, 0
	s_add_i32 m0, s33, 0x14000
	v_mov_b32_e32 v163, v159
	global_load_lds_dwordx4 v158, s[14:15]
	s_add_i32 m0, s33, 0x16000
	s_add_u32 s24, s76, s4
	s_addc_u32 s25, s77, s5
	s_add_i32 s34, s33, 0x2000
	global_load_lds_dwordx4 v162, s[14:15]
	s_mov_b32 m0, s33
	s_add_u32 s4, s24, 0x40000
	global_load_lds_dwordx4 v156, s[24:25]
	s_mov_b32 m0, s34
	s_addc_u32 s5, s25, 0
	s_add_i32 s35, s33, 0x4000
	global_load_lds_dwordx4 v160, s[24:25]
	s_mov_b32 m0, s35
	s_add_i32 s36, s33, 0x6000
	global_load_lds_dwordx4 v156, s[4:5]
	s_mov_b32 m0, s36
	v_mov_b32_e32 v157, v159
	global_load_lds_dwordx4 v160, s[4:5]
	s_movk_i32 s98, 0x100
	v_cmp_gt_u32_e32 vcc, s98, v152
	s_and_saveexec_b64 s[100:101], vcc
	s_cbranch_execz .Lrtab_p8
	s_waitcnt vmcnt(15)
	v_lshl_or_b32 v188, s0, 8, v152
	v_ashrrev_i32_e32 v189, 31, v188
	v_lshlrev_b64 v[188:189], 6, v[188:189]
	s_waitcnt vmcnt(10)
	v_lshl_add_u64 v[204:205], s[12:13], 0, v[188:189]
	global_load_dwordx4 v[188:191], v[204:205], off
	global_load_dwordx4 v[192:195], v[204:205], off offset:32
	global_load_dwordx4 v[196:199], v[204:205], off offset:16
	global_load_dwordx4 v[200:203], v[204:205], off offset:48
	v_mov_b32_e32 v206, 0x358637bd
	s_mov_b32 s98, 0xf800000
	s_waitcnt vmcnt(3)
	v_mov_b32_e32 v204, v188
	s_waitcnt vmcnt(2)
	v_mov_b32_e32 v205, v192
	v_mov_b32_e32 v192, v189
	v_mov_b32_e32 v188, v190
	v_mov_b32_e32 v189, v194
	v_mov_b32_e32 v194, v191
	s_waitcnt vmcnt(1)
	v_mov_b32_e32 v190, v196
	s_waitcnt vmcnt(0)
	v_mov_b32_e32 v191, v200
	v_mov_b32_e32 v200, v197
	v_mov_b32_e32 v196, v198
	v_mov_b32_e32 v197, v202
	v_mov_b32_e32 v202, v199
	v_pk_add_f32 v[192:193], v[204:205], v[192:193]
	v_pk_add_f32 v[188:189], v[188:189], v[194:195]
	v_pk_add_f32 v[190:191], v[190:191], v[200:201]
	v_pk_add_f32 v[194:195], v[196:197], v[202:203]
	v_pk_add_f32 v[188:189], v[192:193], v[188:189]
	v_pk_add_f32 v[190:191], v[190:191], v[194:195]
	s_nop 0
	v_pk_add_f32 v[188:189], v[188:189], v[190:191]
	v_mov_b32_e32 v190, 0x260
	v_add_f32_e32 v188, v188, v189
	v_fmac_f32_e32 v206, 0x3a800000, v188
	v_mul_f32_e32 v188, 0x4f800000, v206
	v_cmp_gt_f32_e32 vcc, s98, v206
	s_nop 1
	v_cndmask_b32_e32 v188, v206, v188, vcc
	v_sqrt_f32_e32 v189, v188
	s_nop 0
	v_add_u32_e32 v191, -1, v189
	v_add_u32_e32 v192, 1, v189
	v_fma_f32 v193, -v191, v189, v188
	v_fma_f32 v194, -v192, v189, v188
	v_cmp_ge_f32_e64 s[98:99], 0, v193
	s_nop 1
	v_cndmask_b32_e64 v189, v189, v191, s[98:99]
	v_cmp_lt_f32_e64 s[98:99], 0, v194
	s_nop 1
	v_cndmask_b32_e64 v189, v189, v192, s[98:99]
	v_mul_f32_e32 v191, 0x37800000, v189
	v_cndmask_b32_e32 v189, v189, v191, vcc
	v_cmp_class_f32_e32 vcc, v188, v190
	v_lshl_add_u32 v191, v152, 2, 0
	s_nop 0
	v_cndmask_b32_e32 v188, v189, v188, vcc
	v_div_scale_f32 v189, s[98:99], v188, v188, 1.0
	v_rcp_f32_e32 v190, v189
	v_div_scale_f32 v192, vcc, 1.0, v188, 1.0
	v_fma_f32 v193, -v189, v190, 1.0
	v_fmac_f32_e32 v190, v193, v190
	v_mul_f32_e32 v193, v192, v190
	v_fma_f32 v194, -v189, v193, v192
	v_fmac_f32_e32 v193, v194, v190
	v_fma_f32 v189, -v189, v193, v192
	v_div_fmas_f32 v189, v189, v190, v193
	v_div_fixup_f32 v188, v189, v188, 1.0
	v_add_u32_e32 v189, 0x20100, v191
	ds_write_b32 v189, v188
.Lrtab_p8:
	s_or_b64 exec, exec, s[100:101]
	v_mov_b32_e32 v161, v159
	s_cmp_eq_u32 s9, 1
	s_mov_b32 s37, 0
	s_waitcnt vmcnt(0)
	v_lshl_add_u64 v[6:7], s[26:27], 0, v[158:159]
	v_lshl_add_u64 v[4:5], s[26:27], 0, v[162:163]
	v_lshl_add_u64 v[0:1], s[24:25], 0, v[156:157]
	s_cselect_b64 s[4:5], -1, 0
	s_cmp_lg_u32 s9, 1
	v_lshl_add_u64 v[2:3], s[24:25], 0, v[160:161]
	s_cbranch_scc1 .LBB0_1316
	s_barrier
